# G1t prologue touches the wave's 8 expert-index rows up front (kept in LDS, acts as an L2 prefetch of the rows re-read in every slice phase)
# baseline (speedup 1.0000x reference)
;     DEVI int* eidx() const { return (int*)(ws + WS_EIDX); }
; #define LAS __attribute__((address_space(3)))
;     const int n16 = lane & 15, kq = lane >> 4;
;     LAS u32x2_t* pl = (LAS u32x2_t*)wl;
;     if (PART != 2) {
;     int e[NTL]; float g[NTL], s_u[NTL], s_v[NTL];
; #pragma unroll
;     for (int t = 0; t < NTL; ++t) { e[t] = eidx[(size_t)r * 128 + (tbase + t) * 16 + n16]; g[t] = gwv[(size_t)r * 128 + (tbase + t) * 16 + n16]; }
; #pragma unroll
;     for (int t = 0; t < NTL; ++t) { s_u[t] = su[e[t]]; s_v[t] = sv[e[t]]; }
;     const unsigned char* up[NTL];
; #pragma unroll
;     for (int t = 0; t < NTL; ++t) up[t] = u8 + (size_t)e[t] * D + kq * 16;
;     const unsigned char* hp = h8 + (n16 < 8 ? (size_t)0 : (size_t)M * D) + (size_t)r * D + kq * 16;
;     f32x4_t acc[NTL];
; #pragma unroll
;     for (int t = 0; t < NTL; ++t) acc[t] = (f32x4_t){0.f, 0.f, 0.f, 0.f};
;     u32x4_t b0[NTL], b1[NTL];
; #pragma unroll
;     for (int t = 0; t < NTL; ++t) { b0[t] = *(const u32x4_t*)(up[t]); b1[t] = *(const u32x4_t*)(up[t] + 64); }
; __global__ void __launch_bounds__(NTHR, 2) mega_fwd(Args a) {
;     ...
;           for (int k0 = 0; gw_ + NGW * k0 < M_P; k0 += 8) {
; #pragma unroll 1
;               for (int k = 0; k < 8; ++k) { const int tok = gw_ + NGW * (k0 + k);
;                   if (tok < M_P) peer_gather_token_t<8, 1>(q_, l_, 0, -1, (LAS float*)nullptr, GARGS, tok, lane_, (LAS unsigned char*)lds + wave * 8192 + k * 1024); }
.LBB0_1084:
	s_or_b64 exec, exec, s[40:41]
	v_readlane_b32 s2, v253, 41
	s_mov_b64 s[6:7], s[74:75]
	s_mov_b64 s[4:5], s[72:73]
	s_mov_b32 s8, s2
	v_mov_b32_e32 v1, v210
	v_readlane_b32 s48, v252, 3
	s_mov_b32 s36, s68
	s_waitcnt lgkmcnt(0)
	s_barrier
	s_cmpk_gt_i32 s48, 0x3fff
	v_and_b32_e32 v116, 15, v1
	v_and_b32_e32 v102, -16, v1
	v_lshlrev_b32_e32 v100, 4, v1
	v_cmp_gt_u32_e64 s[2:3], 16, v1
	s_mul_hi_i32 s46, s8, 0x6c000
	s_mul_i32 s47, s8, 0x6c000
	v_ashrrev_i32_e32 v103, 31, v102
	v_cmp_gt_u32_e32 vcc, 8, v116
	v_lshl_add_u32 v117, v1, 3, s85
	v_ashrrev_i32_e32 v101, 31, v100
	s_cbranch_scc1 .LBB0_1124
	s_lshl_b32 s20, s34, 9
	s_lshl_b32 s21, s34, 10
	s_lshl_b32 s11, s8, 24
	s_add_u32 s56, s6, 0x1fa42100
	s_addc_u32 s57, s7, 0
	s_add_u32 s56, s56, s11
	s_addc_u32 s57, s57, 0
	s_mov_b32 s12, s56
	s_mov_b32 s13, s57
	s_lshl_b32 s11, s48, 9
	s_add_u32 s58, s6, 0x1b292100
	s_addc_u32 s59, s7, 0
	s_add_u32 s58, s58, s11
	s_addc_u32 s59, s59, 0
	s_lshl_b32 s11, s48, 10
	s_add_u32 s60, s6, 0x2fac2100
	s_addc_u32 s61, s7, 0
	s_add_u32 s60, s60, s11
	s_addc_u32 s61, s61, 0
	s_mov_b32 s24, 0x01010101
	s_mov_b32 s25, 0x01010101
	s_mov_b32 s26, 0x02020202
	s_mov_b32 s27, 0x02020202
	s_mov_b32 s28, 0x04040404
	s_mov_b32 s29, 0x04040404
	s_mov_b32 s30, 0x08080808
	s_mov_b32 s31, 0x08080808
	s_mov_b32 s40, 0x10101010
	s_mov_b32 s41, 0x10101010
	s_mov_b32 s42, 0x20202020
	s_mov_b32 s43, 0x20202020
	s_mov_b32 s44, 0x40404040
	s_mov_b32 s45, 0x40404040
	s_mov_b32 s54, 0x80808080
	s_mov_b32 s55, 0x80808080
	v_and_b32_e32 v2, 7, v1
	v_lshrrev_b32_e32 v3, 3, v1
	v_lshlrev_b32_e32 v4, 4, v2
	v_lshlrev_b32_e32 v5, 6, v3
	v_lshlrev_b32_e32 v6, 7, v3
	v_add3_u32 v6, v6, v4, s85
	v_mov_b32_e32 v8, 0x3d000000
	v_mov_b32_e32 v9, 0x3d000000
	v_mov_b32_e32 v118, 0
	v_mov_b32_e32 v119, 0
	ds_write_b32 v6, v118 offset:4
	ds_write_b32 v6, v118 offset:12
	ds_write_b32 v6, v118 offset:1028
	ds_write_b32 v6, v118 offset:1036
	ds_write_b32 v6, v118 offset:2052
	ds_write_b32 v6, v118 offset:2060
	ds_write_b32 v6, v118 offset:3076
	ds_write_b32 v6, v118 offset:3084
	ds_write_b32 v6, v118 offset:4100
	ds_write_b32 v6, v118 offset:4108
	ds_write_b32 v6, v118 offset:5124
	ds_write_b32 v6, v118 offset:5132
	ds_write_b32 v6, v118 offset:6148
	ds_write_b32 v6, v118 offset:6156
	ds_write_b32 v6, v118 offset:7172
	ds_write_b32 v6, v118 offset:7180
	v_lshlrev_b32_e32 v7, 3, v1
	s_mov_b32 s14, s58
	s_mov_b32 s15, s59
	global_load_dwordx2 v[120:121], v7, s[14:15]
	s_add_u32 s14, s14, s20
	s_addc_u32 s15, s15, 0
	global_load_dwordx2 v[124:125], v7, s[14:15]
	s_add_u32 s14, s14, s20
	s_addc_u32 s15, s15, 0
	global_load_dwordx2 v[128:129], v7, s[14:15]
	s_add_u32 s14, s14, s20
	s_addc_u32 s15, s15, 0
	global_load_dwordx2 v[132:133], v7, s[14:15]
	s_add_u32 s14, s14, s20
	s_addc_u32 s15, s15, 0
	global_load_dwordx2 v[136:137], v7, s[14:15]
	s_add_u32 s14, s14, s20
	s_addc_u32 s15, s15, 0
	global_load_dwordx2 v[140:141], v7, s[14:15]
	s_add_u32 s14, s14, s20
	s_addc_u32 s15, s15, 0
	global_load_dwordx2 v[144:145], v7, s[14:15]
	s_add_u32 s14, s14, s20
	s_addc_u32 s15, s15, 0
	global_load_dwordx2 v[148:149], v7, s[14:15]
	s_lshr_b32 s9, s85, 1
	s_add_u32 s9, s9, 0x10000
	v_add_u32_e32 v7, s9, v7
	s_waitcnt vmcnt(0)
	ds_write_b64 v7, v[120:121] offset:0
	ds_write_b64 v7, v[124:125] offset:512
	ds_write_b64 v7, v[128:129] offset:1024
	ds_write_b64 v7, v[132:133] offset:1536
	ds_write_b64 v7, v[136:137] offset:2048
	ds_write_b64 v7, v[140:141] offset:2560
	ds_write_b64 v7, v[144:145] offset:3072
	ds_write_b64 v7, v[148:149] offset:3584
	s_waitcnt lgkmcnt(0)
	global_load_dwordx4 v[84:87], v5, s[58:59] offset:0
	global_load_dwordx4 v[88:91], v5, s[58:59] offset:16
	global_load_dwordx4 v[92:95], v5, s[58:59] offset:32
	global_load_dwordx4 v[96:99], v5, s[58:59] offset:48
	s_waitcnt vmcnt(0)
	v_lshl_add_u32 v68, v84, 10, v4
	v_lshl_add_u32 v69, v85, 10, v4
	v_lshl_add_u32 v70, v86, 10, v4
	v_lshl_add_u32 v71, v87, 10, v4
	v_lshl_add_u32 v72, v88, 10, v4
	v_lshl_add_u32 v73, v89, 10, v4
	v_lshl_add_u32 v74, v90, 10, v4
	v_lshl_add_u32 v75, v91, 10, v4
	v_lshl_add_u32 v76, v92, 10, v4
	v_lshl_add_u32 v77, v93, 10, v4
	v_lshl_add_u32 v78, v94, 10, v4
	v_lshl_add_u32 v79, v95, 10, v4
	v_lshl_add_u32 v80, v96, 10, v4
	v_lshl_add_u32 v81, v97, 10, v4
	v_lshl_add_u32 v82, v98, 10, v4
	v_lshl_add_u32 v83, v99, 10, v4
	s_add_u32 s18, s60, 0x1100000
	s_addc_u32 s19, s61, 0
	global_load_dwordx4 v[180:183], v4, s[60:61]
	global_load_dwordx4 v[184:187], v4, s[18:19]
	s_add_u32 s14, s58, s20
	s_addc_u32 s15, s59, 0
	global_load_dwordx4 v[84:87], v5, s[14:15] offset:0
	global_load_dwordx4 v[88:91], v5, s[14:15] offset:16
	global_load_dwordx4 v[92:95], v5, s[14:15] offset:32
	global_load_dwordx4 v[96:99], v5, s[14:15] offset:48
	global_load_dwordx4 v[120:123], v68, s[12:13]
	global_load_dwordx4 v[124:127], v69, s[12:13]
	global_load_dwordx4 v[128:131], v70, s[12:13]
	global_load_dwordx4 v[132:135], v71, s[12:13]
	global_load_dwordx4 v[136:139], v72, s[12:13]
	global_load_dwordx4 v[140:143], v73, s[12:13]
	global_load_dwordx4 v[144:147], v74, s[12:13]
	global_load_dwordx4 v[148:151], v75, s[12:13]
	global_load_dwordx4 v[152:155], v76, s[12:13]
	global_load_dwordx4 v[156:159], v77, s[12:13]
	global_load_dwordx4 v[160:163], v78, s[12:13]
	global_load_dwordx4 v[164:167], v79, s[12:13]
	global_load_dwordx4 v[168:171], v80, s[12:13]
	global_load_dwordx4 v[172:175], v81, s[12:13]
	global_load_dwordx4 v[188:191], v82, s[12:13]
	global_load_dwordx4 v[192:195], v83, s[12:13]
	s_mov_b32 s22, 0
